# adds: P5 chunk-state scan with all 32 chunk loads in flight; P11 final-norm weights loaded early so the last stores are not serialized behind loads
# speedup vs baseline: 1.0088x; 1.0066x over previous
; __device__ __forceinline__ unsigned cvt_pk_bf16(float lo, float hi) { unsigned r; asm volatile("v_cvt_pk_bf16_f32 %0, %1, %2" : "=v"(r) : "v"(lo), "v"(hi)); return r; }
; __device__ __forceinline__ void mlstm_state_scan(const Frame& F) {
;     ...
;     const int gt = F.bid * 512 + F.tid, GT = F.G * 512;
;     typedef float f32x2 __attribute__((ext_vector_type(2)));
;     for (int e2 = gt; e2 < 131072; e2 += GT) { const int h = e2 >> 15;
;         f32x2 C = (f32x2){0.f, 0.f};
; #pragma unroll 1
;         for (int c0 = 0; c0 < NCH; c0 += 8) { f32x2 u[8];
; #pragma unroll
;             for (int k = 0; k < 8; ++k) u[k] = *(const f32x2*)(U + (size_t)(c0 + k) * 262144 + (size_t)e2 * 2);
; #pragma unroll
;             for (int k = 0; k < 8; ++k) { *(unsigned*)(CST + (size_t)(c0 + k) * 262144 + (size_t)e2 * 2) = cvt_pk_bf16(C[0], C[1]); C = C * sdec[h * 32 + c0 + k] + u[k]; } }
;         *(f32x2*)(F.out + O_CP + (size_t)e2 * 2) = C; }
.LBB0_679:
	v_ashrrev_i32_e32 v5, 10, v4
	v_lshlrev_b32_e32 v5, 2, v5
	v_and_b32_e32 v5, 0xffffff80, v5
	v_add_u32_e32 v5, 0, v5
	v_mov_b32_e32 v10, 0
	v_mov_b32_e32 v11, v10
	v_lshl_add_u64 v[12:13], s[84:85], 0, v[0:1]
	v_lshl_add_u64 v[6:7], s[84:85], 0, v[2:3]
	v_add_co_u32_e32 v14, vcc, 0x17dc0000, v12
	s_nop 1
	v_addc_co_u32_e32 v15, vcc, 0, v13, vcc
	global_load_dwordx2 v[40:41], v[14:15], off offset:256
	v_add_co_u32_e32 v14, vcc, 0x17ec0000, v12
	s_nop 1
	v_addc_co_u32_e32 v15, vcc, 0, v13, vcc
	global_load_dwordx2 v[42:43], v[14:15], off offset:256
	v_add_co_u32_e32 v14, vcc, 0x17fc0000, v12
	s_nop 1
	v_addc_co_u32_e32 v15, vcc, 0, v13, vcc
	global_load_dwordx2 v[44:45], v[14:15], off offset:256
	v_add_co_u32_e32 v14, vcc, 0x180c0000, v12
	s_nop 1
	v_addc_co_u32_e32 v15, vcc, 0, v13, vcc
	global_load_dwordx2 v[46:47], v[14:15], off offset:256
	v_add_co_u32_e32 v14, vcc, 0x181c0000, v12
	s_nop 1
	v_addc_co_u32_e32 v15, vcc, 0, v13, vcc
	global_load_dwordx2 v[48:49], v[14:15], off offset:256
	v_add_co_u32_e32 v14, vcc, 0x182c0000, v12
	s_nop 1
	v_addc_co_u32_e32 v15, vcc, 0, v13, vcc
	global_load_dwordx2 v[50:51], v[14:15], off offset:256
	v_add_co_u32_e32 v14, vcc, 0x183c0000, v12
	s_nop 1
	v_addc_co_u32_e32 v15, vcc, 0, v13, vcc
	global_load_dwordx2 v[52:53], v[14:15], off offset:256
	v_add_co_u32_e32 v14, vcc, 0x184c0000, v12
	s_nop 1
	v_addc_co_u32_e32 v15, vcc, 0, v13, vcc
	global_load_dwordx2 v[54:55], v[14:15], off offset:256
	v_add_co_u32_e32 v14, vcc, 0x185c0000, v12
	s_nop 1
	v_addc_co_u32_e32 v15, vcc, 0, v13, vcc
	global_load_dwordx2 v[56:57], v[14:15], off offset:256
	v_add_co_u32_e32 v14, vcc, 0x186c0000, v12
	s_nop 1
	v_addc_co_u32_e32 v15, vcc, 0, v13, vcc
	global_load_dwordx2 v[58:59], v[14:15], off offset:256
	v_add_co_u32_e32 v14, vcc, 0x187c0000, v12
	s_nop 1
	v_addc_co_u32_e32 v15, vcc, 0, v13, vcc
	global_load_dwordx2 v[60:61], v[14:15], off offset:256
	v_add_co_u32_e32 v14, vcc, 0x188c0000, v12
	s_nop 1
	v_addc_co_u32_e32 v15, vcc, 0, v13, vcc
	global_load_dwordx2 v[62:63], v[14:15], off offset:256
	v_add_co_u32_e32 v14, vcc, 0x189c0000, v12
	s_nop 1
	v_addc_co_u32_e32 v15, vcc, 0, v13, vcc
	global_load_dwordx2 v[64:65], v[14:15], off offset:256
	v_add_co_u32_e32 v14, vcc, 0x18ac0000, v12
	s_nop 1
	v_addc_co_u32_e32 v15, vcc, 0, v13, vcc
	global_load_dwordx2 v[66:67], v[14:15], off offset:256
	v_add_co_u32_e32 v14, vcc, 0x18bc0000, v12
	s_nop 1
	v_addc_co_u32_e32 v15, vcc, 0, v13, vcc
	global_load_dwordx2 v[68:69], v[14:15], off offset:256
	v_add_co_u32_e32 v14, vcc, 0x18cc0000, v12
	s_nop 1
	v_addc_co_u32_e32 v15, vcc, 0, v13, vcc
	global_load_dwordx2 v[70:71], v[14:15], off offset:256
	v_add_co_u32_e32 v14, vcc, 0x18dc0000, v12
	s_nop 1
	v_addc_co_u32_e32 v15, vcc, 0, v13, vcc
	global_load_dwordx2 v[72:73], v[14:15], off offset:256
	v_add_co_u32_e32 v14, vcc, 0x18ec0000, v12
	s_nop 1
	v_addc_co_u32_e32 v15, vcc, 0, v13, vcc
	global_load_dwordx2 v[74:75], v[14:15], off offset:256
	v_add_co_u32_e32 v14, vcc, 0x18fc0000, v12
	s_nop 1
	v_addc_co_u32_e32 v15, vcc, 0, v13, vcc
	global_load_dwordx2 v[76:77], v[14:15], off offset:256
	v_add_co_u32_e32 v14, vcc, 0x190c0000, v12
	s_nop 1
	v_addc_co_u32_e32 v15, vcc, 0, v13, vcc
	global_load_dwordx2 v[78:79], v[14:15], off offset:256
	v_add_co_u32_e32 v14, vcc, 0x191c0000, v12
	s_nop 1
	v_addc_co_u32_e32 v15, vcc, 0, v13, vcc
	global_load_dwordx2 v[80:81], v[14:15], off offset:256
	v_add_co_u32_e32 v14, vcc, 0x192c0000, v12
	s_nop 1
	v_addc_co_u32_e32 v15, vcc, 0, v13, vcc
	global_load_dwordx2 v[82:83], v[14:15], off offset:256
	v_add_co_u32_e32 v14, vcc, 0x193c0000, v12
	s_nop 1
	v_addc_co_u32_e32 v15, vcc, 0, v13, vcc
	global_load_dwordx2 v[84:85], v[14:15], off offset:256
	v_add_co_u32_e32 v14, vcc, 0x194c0000, v12
	s_nop 1
	v_addc_co_u32_e32 v15, vcc, 0, v13, vcc
	global_load_dwordx2 v[86:87], v[14:15], off offset:256
	v_add_co_u32_e32 v14, vcc, 0x195c0000, v12
	s_nop 1
	v_addc_co_u32_e32 v15, vcc, 0, v13, vcc
	global_load_dwordx2 v[88:89], v[14:15], off offset:256
	v_add_co_u32_e32 v14, vcc, 0x196c0000, v12
	s_nop 1
	v_addc_co_u32_e32 v15, vcc, 0, v13, vcc
	global_load_dwordx2 v[90:91], v[14:15], off offset:256
	v_add_co_u32_e32 v14, vcc, 0x197c0000, v12
	s_nop 1
	v_addc_co_u32_e32 v15, vcc, 0, v13, vcc
	global_load_dwordx2 v[92:93], v[14:15], off offset:256
	v_add_co_u32_e32 v14, vcc, 0x198c0000, v12
	s_nop 1
	v_addc_co_u32_e32 v15, vcc, 0, v13, vcc
	global_load_dwordx2 v[94:95], v[14:15], off offset:256
	v_add_co_u32_e32 v14, vcc, 0x199c0000, v12
	s_nop 1
	v_addc_co_u32_e32 v15, vcc, 0, v13, vcc
	global_load_dwordx2 v[96:97], v[14:15], off offset:256
	v_add_co_u32_e32 v14, vcc, 0x19ac0000, v12
	s_nop 1
	v_addc_co_u32_e32 v15, vcc, 0, v13, vcc
	global_load_dwordx2 v[98:99], v[14:15], off offset:256
	v_add_co_u32_e32 v14, vcc, 0x19bc0000, v12
	s_nop 1
	v_addc_co_u32_e32 v15, vcc, 0, v13, vcc
	global_load_dwordx2 v[100:101], v[14:15], off offset:256
	v_add_co_u32_e32 v14, vcc, 0x19cc0000, v12
	s_nop 1
	v_addc_co_u32_e32 v15, vcc, 0, v13, vcc
	global_load_dwordx2 v[102:103], v[14:15], off offset:256
	v_cvt_pk_bf16_f32 v35, v10, v11
	ds_read_b32 v34, v5
	v_add_co_u32_e32 v32, vcc, 0x19de0000, v6
	s_waitcnt vmcnt(31) lgkmcnt(0)
	v_pk_fma_f32 v[10:11], v[10:11], v[34:35], v[40:41] op_sel_hi:[1,0,1]
	v_addc_co_u32_e32 v33, vcc, 0, v7, vcc
	global_store_dword v[32:33], v35, off offset:256
	v_cvt_pk_bf16_f32 v35, v10, v11
	ds_read_b32 v34, v5 offset:4
	v_add_co_u32_e32 v32, vcc, 0x19e60000, v6
	s_waitcnt vmcnt(31) lgkmcnt(0)
; __device__ __forceinline__ unsigned cvt_pk_bf16(float lo, float hi) { unsigned r; asm volatile("v_cvt_pk_bf16_f32 %0, %1, %2" : "=v"(r) : "v"(lo), "v"(hi)); return r; }
; __device__ __forceinline__ void mlstm_state_scan(const Frame& F) {
;     ...
;     for (int e2 = gt; e2 < 131072; e2 += GT) { const int h = e2 >> 15;
;         f32x2 C = (f32x2){0.f, 0.f};
; #pragma unroll 1
;         for (int c0 = 0; c0 < NCH; c0 += 8) { f32x2 u[8];
; #pragma unroll
;             for (int k = 0; k < 8; ++k) u[k] = *(const f32x2*)(U + (size_t)(c0 + k) * 262144 + (size_t)e2 * 2);
; #pragma unroll
;             for (int k = 0; k < 8; ++k) { *(unsigned*)(CST + (size_t)(c0 + k) * 262144 + (size_t)e2 * 2) = cvt_pk_bf16(C[0], C[1]); C = C * sdec[h * 32 + c0 + k] + u[k]; } }
	v_pk_fma_f32 v[10:11], v[10:11], v[34:35], v[42:43] op_sel_hi:[1,0,1]
	v_addc_co_u32_e32 v33, vcc, 0, v7, vcc
	global_store_dword v[32:33], v35, off offset:256
	v_cvt_pk_bf16_f32 v35, v10, v11
	ds_read_b32 v34, v5 offset:8
	v_add_co_u32_e32 v32, vcc, 0x19ee0000, v6
	s_waitcnt vmcnt(31) lgkmcnt(0)
	v_pk_fma_f32 v[10:11], v[10:11], v[34:35], v[44:45] op_sel_hi:[1,0,1]
	v_addc_co_u32_e32 v33, vcc, 0, v7, vcc
	global_store_dword v[32:33], v35, off offset:256
	v_cvt_pk_bf16_f32 v35, v10, v11
	ds_read_b32 v34, v5 offset:12
	v_add_co_u32_e32 v32, vcc, 0x19f60000, v6
	s_waitcnt vmcnt(31) lgkmcnt(0)
	v_pk_fma_f32 v[10:11], v[10:11], v[34:35], v[46:47] op_sel_hi:[1,0,1]
	v_addc_co_u32_e32 v33, vcc, 0, v7, vcc
	global_store_dword v[32:33], v35, off offset:256
	v_cvt_pk_bf16_f32 v35, v10, v11
	ds_read_b32 v34, v5 offset:16
	v_add_co_u32_e32 v32, vcc, 0x19fe0000, v6
	s_waitcnt vmcnt(31) lgkmcnt(0)
	v_pk_fma_f32 v[10:11], v[10:11], v[34:35], v[48:49] op_sel_hi:[1,0,1]
	v_addc_co_u32_e32 v33, vcc, 0, v7, vcc
	global_store_dword v[32:33], v35, off offset:256
	v_cvt_pk_bf16_f32 v35, v10, v11
	ds_read_b32 v34, v5 offset:20
	v_add_co_u32_e32 v32, vcc, 0x1a060000, v6
	s_waitcnt vmcnt(31) lgkmcnt(0)
	v_pk_fma_f32 v[10:11], v[10:11], v[34:35], v[50:51] op_sel_hi:[1,0,1]
	v_addc_co_u32_e32 v33, vcc, 0, v7, vcc
	global_store_dword v[32:33], v35, off offset:256
	v_cvt_pk_bf16_f32 v35, v10, v11
	ds_read_b32 v34, v5 offset:24
	v_add_co_u32_e32 v32, vcc, 0x1a0e0000, v6
	s_waitcnt vmcnt(31) lgkmcnt(0)
	v_pk_fma_f32 v[10:11], v[10:11], v[34:35], v[52:53] op_sel_hi:[1,0,1]
	v_addc_co_u32_e32 v33, vcc, 0, v7, vcc
	global_store_dword v[32:33], v35, off offset:256
	v_cvt_pk_bf16_f32 v35, v10, v11
	ds_read_b32 v34, v5 offset:28
	v_add_co_u32_e32 v32, vcc, 0x1a160000, v6
	s_waitcnt vmcnt(31) lgkmcnt(0)
	v_pk_fma_f32 v[10:11], v[10:11], v[34:35], v[54:55] op_sel_hi:[1,0,1]
	v_addc_co_u32_e32 v33, vcc, 0, v7, vcc
	global_store_dword v[32:33], v35, off offset:256
	v_cvt_pk_bf16_f32 v35, v10, v11
	ds_read_b32 v34, v5 offset:32
	v_add_co_u32_e32 v32, vcc, 0x1a1e0000, v6
	s_waitcnt vmcnt(31) lgkmcnt(0)
	v_pk_fma_f32 v[10:11], v[10:11], v[34:35], v[56:57] op_sel_hi:[1,0,1]
	v_addc_co_u32_e32 v33, vcc, 0, v7, vcc
	global_store_dword v[32:33], v35, off offset:256
	v_cvt_pk_bf16_f32 v35, v10, v11
	ds_read_b32 v34, v5 offset:36
	v_add_co_u32_e32 v32, vcc, 0x1a260000, v6
	s_waitcnt vmcnt(31) lgkmcnt(0)
	v_pk_fma_f32 v[10:11], v[10:11], v[34:35], v[58:59] op_sel_hi:[1,0,1]
	v_addc_co_u32_e32 v33, vcc, 0, v7, vcc
	global_store_dword v[32:33], v35, off offset:256
	v_cvt_pk_bf16_f32 v35, v10, v11
	ds_read_b32 v34, v5 offset:40
	v_add_co_u32_e32 v32, vcc, 0x1a2e0000, v6
	s_waitcnt vmcnt(31) lgkmcnt(0)
	v_pk_fma_f32 v[10:11], v[10:11], v[34:35], v[60:61] op_sel_hi:[1,0,1]
	v_addc_co_u32_e32 v33, vcc, 0, v7, vcc
	global_store_dword v[32:33], v35, off offset:256
	v_cvt_pk_bf16_f32 v35, v10, v11
	ds_read_b32 v34, v5 offset:44
	v_add_co_u32_e32 v32, vcc, 0x1a360000, v6
	s_waitcnt vmcnt(31) lgkmcnt(0)
	v_pk_fma_f32 v[10:11], v[10:11], v[34:35], v[62:63] op_sel_hi:[1,0,1]
	v_addc_co_u32_e32 v33, vcc, 0, v7, vcc
	global_store_dword v[32:33], v35, off offset:256
	v_cvt_pk_bf16_f32 v35, v10, v11
	ds_read_b32 v34, v5 offset:48
	v_add_co_u32_e32 v32, vcc, 0x1a3e0000, v6
	s_waitcnt vmcnt(31) lgkmcnt(0)
	v_pk_fma_f32 v[10:11], v[10:11], v[34:35], v[64:65] op_sel_hi:[1,0,1]
	v_addc_co_u32_e32 v33, vcc, 0, v7, vcc
	global_store_dword v[32:33], v35, off offset:256
	v_cvt_pk_bf16_f32 v35, v10, v11
	ds_read_b32 v34, v5 offset:52
	v_add_co_u32_e32 v32, vcc, 0x1a460000, v6
	s_waitcnt vmcnt(31) lgkmcnt(0)
	v_pk_fma_f32 v[10:11], v[10:11], v[34:35], v[66:67] op_sel_hi:[1,0,1]
	v_addc_co_u32_e32 v33, vcc, 0, v7, vcc
	global_store_dword v[32:33], v35, off offset:256
	v_cvt_pk_bf16_f32 v35, v10, v11
	ds_read_b32 v34, v5 offset:56
	v_add_co_u32_e32 v32, vcc, 0x1a4e0000, v6
	s_waitcnt vmcnt(31) lgkmcnt(0)
	v_pk_fma_f32 v[10:11], v[10:11], v[34:35], v[68:69] op_sel_hi:[1,0,1]
	v_addc_co_u32_e32 v33, vcc, 0, v7, vcc
	global_store_dword v[32:33], v35, off offset:256
	v_cvt_pk_bf16_f32 v35, v10, v11
	ds_read_b32 v34, v5 offset:60
	v_add_co_u32_e32 v32, vcc, 0x1a560000, v6
	s_waitcnt vmcnt(31) lgkmcnt(0)
	v_pk_fma_f32 v[10:11], v[10:11], v[34:35], v[70:71] op_sel_hi:[1,0,1]
	v_addc_co_u32_e32 v33, vcc, 0, v7, vcc
	global_store_dword v[32:33], v35, off offset:256
	v_cvt_pk_bf16_f32 v35, v10, v11
	ds_read_b32 v34, v5 offset:64
	v_add_co_u32_e32 v32, vcc, 0x1a5e0000, v6
	s_waitcnt vmcnt(31) lgkmcnt(0)
	v_pk_fma_f32 v[10:11], v[10:11], v[34:35], v[72:73] op_sel_hi:[1,0,1]
	v_addc_co_u32_e32 v33, vcc, 0, v7, vcc
	global_store_dword v[32:33], v35, off offset:256
	v_cvt_pk_bf16_f32 v35, v10, v11
	ds_read_b32 v34, v5 offset:68
	v_add_co_u32_e32 v32, vcc, 0x1a660000, v6
	s_waitcnt vmcnt(31) lgkmcnt(0)
; __device__ __forceinline__ unsigned cvt_pk_bf16(float lo, float hi) { unsigned r; asm volatile("v_cvt_pk_bf16_f32 %0, %1, %2" : "=v"(r) : "v"(lo), "v"(hi)); return r; }
; __device__ __forceinline__ void mlstm_state_scan(const Frame& F) {
;     ...
;     for (int e2 = gt; e2 < 131072; e2 += GT) { const int h = e2 >> 15;
;         f32x2 C = (f32x2){0.f, 0.f};
; #pragma unroll 1
;         for (int c0 = 0; c0 < NCH; c0 += 8) { f32x2 u[8];
; #pragma unroll
;             for (int k = 0; k < 8; ++k) u[k] = *(const f32x2*)(U + (size_t)(c0 + k) * 262144 + (size_t)e2 * 2);
; #pragma unroll
;             for (int k = 0; k < 8; ++k) { *(unsigned*)(CST + (size_t)(c0 + k) * 262144 + (size_t)e2 * 2) = cvt_pk_bf16(C[0], C[1]); C = C * sdec[h * 32 + c0 + k] + u[k]; } }
;         *(f32x2*)(F.out + O_CP + (size_t)e2 * 2) = C; }
	v_pk_fma_f32 v[10:11], v[10:11], v[34:35], v[74:75] op_sel_hi:[1,0,1]
	v_addc_co_u32_e32 v33, vcc, 0, v7, vcc
	global_store_dword v[32:33], v35, off offset:256
	v_cvt_pk_bf16_f32 v35, v10, v11
	ds_read_b32 v34, v5 offset:72
	v_add_co_u32_e32 v32, vcc, 0x1a6e0000, v6
	s_waitcnt vmcnt(31) lgkmcnt(0)
	v_pk_fma_f32 v[10:11], v[10:11], v[34:35], v[76:77] op_sel_hi:[1,0,1]
	v_addc_co_u32_e32 v33, vcc, 0, v7, vcc
	global_store_dword v[32:33], v35, off offset:256
	v_cvt_pk_bf16_f32 v35, v10, v11
	ds_read_b32 v34, v5 offset:76
	v_add_co_u32_e32 v32, vcc, 0x1a760000, v6
	s_waitcnt vmcnt(31) lgkmcnt(0)
	v_pk_fma_f32 v[10:11], v[10:11], v[34:35], v[78:79] op_sel_hi:[1,0,1]
	v_addc_co_u32_e32 v33, vcc, 0, v7, vcc
	global_store_dword v[32:33], v35, off offset:256
	v_cvt_pk_bf16_f32 v35, v10, v11
	ds_read_b32 v34, v5 offset:80
	v_add_co_u32_e32 v32, vcc, 0x1a7e0000, v6
	s_waitcnt vmcnt(31) lgkmcnt(0)
	v_pk_fma_f32 v[10:11], v[10:11], v[34:35], v[80:81] op_sel_hi:[1,0,1]
	v_addc_co_u32_e32 v33, vcc, 0, v7, vcc
	global_store_dword v[32:33], v35, off offset:256
	v_cvt_pk_bf16_f32 v35, v10, v11
	ds_read_b32 v34, v5 offset:84
	v_add_co_u32_e32 v32, vcc, 0x1a860000, v6
	s_waitcnt vmcnt(31) lgkmcnt(0)
	v_pk_fma_f32 v[10:11], v[10:11], v[34:35], v[82:83] op_sel_hi:[1,0,1]
	v_addc_co_u32_e32 v33, vcc, 0, v7, vcc
	global_store_dword v[32:33], v35, off offset:256
	v_cvt_pk_bf16_f32 v35, v10, v11
	ds_read_b32 v34, v5 offset:88
	v_add_co_u32_e32 v32, vcc, 0x1a8e0000, v6
	s_waitcnt vmcnt(31) lgkmcnt(0)
	v_pk_fma_f32 v[10:11], v[10:11], v[34:35], v[84:85] op_sel_hi:[1,0,1]
	v_addc_co_u32_e32 v33, vcc, 0, v7, vcc
	global_store_dword v[32:33], v35, off offset:256
	v_cvt_pk_bf16_f32 v35, v10, v11
	ds_read_b32 v34, v5 offset:92
	v_add_co_u32_e32 v32, vcc, 0x1a960000, v6
	s_waitcnt vmcnt(31) lgkmcnt(0)
	v_pk_fma_f32 v[10:11], v[10:11], v[34:35], v[86:87] op_sel_hi:[1,0,1]
	v_addc_co_u32_e32 v33, vcc, 0, v7, vcc
	global_store_dword v[32:33], v35, off offset:256
	v_cvt_pk_bf16_f32 v35, v10, v11
	ds_read_b32 v34, v5 offset:96
	v_add_co_u32_e32 v32, vcc, 0x1a9e0000, v6
	s_waitcnt vmcnt(31) lgkmcnt(0)
	v_pk_fma_f32 v[10:11], v[10:11], v[34:35], v[88:89] op_sel_hi:[1,0,1]
	v_addc_co_u32_e32 v33, vcc, 0, v7, vcc
	global_store_dword v[32:33], v35, off offset:256
	v_cvt_pk_bf16_f32 v35, v10, v11
	ds_read_b32 v34, v5 offset:100
	v_add_co_u32_e32 v32, vcc, 0x1aa60000, v6
	s_waitcnt vmcnt(31) lgkmcnt(0)
	v_pk_fma_f32 v[10:11], v[10:11], v[34:35], v[90:91] op_sel_hi:[1,0,1]
	v_addc_co_u32_e32 v33, vcc, 0, v7, vcc
	global_store_dword v[32:33], v35, off offset:256
	v_cvt_pk_bf16_f32 v35, v10, v11
	ds_read_b32 v34, v5 offset:104
	v_add_co_u32_e32 v32, vcc, 0x1aae0000, v6
	s_waitcnt vmcnt(31) lgkmcnt(0)
	v_pk_fma_f32 v[10:11], v[10:11], v[34:35], v[92:93] op_sel_hi:[1,0,1]
	v_addc_co_u32_e32 v33, vcc, 0, v7, vcc
	global_store_dword v[32:33], v35, off offset:256
	v_cvt_pk_bf16_f32 v35, v10, v11
	ds_read_b32 v34, v5 offset:108
	v_add_co_u32_e32 v32, vcc, 0x1ab60000, v6
	s_waitcnt vmcnt(31) lgkmcnt(0)
	v_pk_fma_f32 v[10:11], v[10:11], v[34:35], v[94:95] op_sel_hi:[1,0,1]
	v_addc_co_u32_e32 v33, vcc, 0, v7, vcc
	global_store_dword v[32:33], v35, off offset:256
	v_cvt_pk_bf16_f32 v35, v10, v11
	ds_read_b32 v34, v5 offset:112
	v_add_co_u32_e32 v32, vcc, 0x1abe0000, v6
	s_waitcnt vmcnt(31) lgkmcnt(0)
	v_pk_fma_f32 v[10:11], v[10:11], v[34:35], v[96:97] op_sel_hi:[1,0,1]
	v_addc_co_u32_e32 v33, vcc, 0, v7, vcc
	global_store_dword v[32:33], v35, off offset:256
	v_cvt_pk_bf16_f32 v35, v10, v11
	ds_read_b32 v34, v5 offset:116
	v_add_co_u32_e32 v32, vcc, 0x1ac60000, v6
	s_waitcnt vmcnt(31) lgkmcnt(0)
	v_pk_fma_f32 v[10:11], v[10:11], v[34:35], v[98:99] op_sel_hi:[1,0,1]
	v_addc_co_u32_e32 v33, vcc, 0, v7, vcc
	global_store_dword v[32:33], v35, off offset:256
	v_cvt_pk_bf16_f32 v35, v10, v11
	ds_read_b32 v34, v5 offset:120
	v_add_co_u32_e32 v32, vcc, 0x1ace0000, v6
	s_waitcnt vmcnt(31) lgkmcnt(0)
	v_pk_fma_f32 v[10:11], v[10:11], v[34:35], v[100:101] op_sel_hi:[1,0,1]
	v_addc_co_u32_e32 v33, vcc, 0, v7, vcc
	global_store_dword v[32:33], v35, off offset:256
	v_cvt_pk_bf16_f32 v35, v10, v11
	ds_read_b32 v34, v5 offset:124
	v_add_co_u32_e32 v32, vcc, 0x1ad60000, v6
	s_waitcnt vmcnt(31) lgkmcnt(0)
	v_pk_fma_f32 v[10:11], v[10:11], v[34:35], v[102:103] op_sel_hi:[1,0,1]
	v_addc_co_u32_e32 v33, vcc, 0, v7, vcc
	global_store_dword v[32:33], v35, off offset:256
	v_ashrrev_i32_e32 v5, 31, v4
	v_lshl_add_u64 v[6:7], v[4:5], 3, s[2:3]
	v_add_u32_e32 v4, s20, v4
	v_cmp_lt_i32_e32 vcc, s14, v4
	v_lshl_add_u64 v[0:1], v[0:1], 0, s[4:5]
	s_or_b64 s[8:9], vcc, s[8:9]
	v_lshl_add_u64 v[2:3], v[2:3], 0, s[6:7]
	global_store_dwordx2 v[6:7], v[10:11], off
	s_andn2_b64 exec, exec, s[8:9]
	s_cbranch_execnz .LBB0_679

; __device__ __forceinline__ void final_norm_phase(const Frame& F, int rlo) {
;     ...
; #pragma unroll
;         for (int i = 0; i < 8; ++i) ss += xv[i][0] * xv[i][0] + xv[i][1] * xv[i][1] + xv[i][2] * xv[i][2] + xv[i][3] * xv[i][3];
;         ss = wave_sum(ss); const float rstd = rsqrtf(ss * (1.f / D) + EPS);
; #pragma unroll
;         for (int i = 0; i < 8; ++i) { const f32x4 w = ((const f32x4*)nw)[i * 64 + F.lane]; xr[i * 64 + F.lane] = xv[i] * rstd * w; } }
.LBB0_1241:
	s_waitcnt vmcnt(7)
	v_mul_f32_e32 v32, v29, v29
	s_waitcnt vmcnt(6)
	v_mul_f32_e32 v33, v25, v25
	v_fmac_f32_e32 v32, v28, v28
	v_fmac_f32_e32 v33, v24, v24
	v_fmac_f32_e32 v32, v30, v30
	v_fmac_f32_e32 v33, v26, v26
	v_fmac_f32_e32 v32, v31, v31
	v_fmac_f32_e32 v33, v27, v27
	v_add_f32_e32 v32, v32, v33
	s_waitcnt vmcnt(5)
	v_mul_f32_e32 v33, v21, v21
	v_fmac_f32_e32 v33, v20, v20
	v_fmac_f32_e32 v33, v22, v22
	v_fmac_f32_e32 v33, v23, v23
	v_add_f32_e32 v36, v33, v32
	global_load_dwordx4 v[32:35], v[182:183], off
	s_waitcnt vmcnt(5)
	v_mul_f32_e32 v37, v17, v17
	s_waitcnt vmcnt(3)
	v_pk_mul_f32 v[48:49], v[8:9], v[8:9]
	v_pk_mul_f32 v[50:51], v[12:13], v[12:13]
	v_fmac_f32_e32 v37, v16, v16
	v_pk_mul_f32 v[44:45], v[10:11], v[10:11]
	v_pk_mul_f32 v[46:47], v[14:15], v[14:15]
	v_mov_b32_e32 v52, v48
	v_mov_b32_e32 v53, v50
	v_mov_b32_e32 v50, v49
	v_fmac_f32_e32 v37, v18, v18
	v_pk_add_f32 v[48:49], v[52:53], v[50:51]
	v_mov_b32_e32 v50, v44
	v_mov_b32_e32 v51, v46
	v_fmac_f32_e32 v37, v19, v19
	v_pk_add_f32 v[48:49], v[50:51], v[48:49]
	v_mov_b32_e32 v46, v45
	v_add_f32_e32 v54, v37, v36
	v_pk_add_f32 v[44:45], v[46:47], v[48:49]
	s_waitcnt vmcnt(1)
	v_pk_mul_f32 v[40:41], v[0:1], v[0:1]
	v_pk_mul_f32 v[42:43], v[4:5], v[4:5]
	v_add_f32_e32 v45, v45, v54
	v_pk_mul_f32 v[36:37], v[2:3], v[2:3]
	v_pk_mul_f32 v[38:39], v[6:7], v[6:7]
	v_add_f32_e32 v46, v44, v45
	v_mov_b32_e32 v44, v40
	v_mov_b32_e32 v45, v42
	v_mov_b32_e32 v42, v41
	v_pk_add_f32 v[40:41], v[44:45], v[42:43]
	v_mov_b32_e32 v42, v36
	v_mov_b32_e32 v43, v38
	v_pk_add_f32 v[40:41], v[42:43], v[40:41]
	v_mov_b32_e32 v38, v37
	v_pk_add_f32 v[36:37], v[38:39], v[40:41]
	s_add_i32 s0, s0, s4
	v_add_f32_e32 v37, v37, v46
	global_load_dwordx4 v[40:43], v[184:185], off
	global_load_dwordx4 v[44:47], v[186:187], off
	global_load_dwordx4 v[48:51], v[188:189], off
	v_add_f32_e32 v36, v36, v37
	ds_bpermute_b32 v37, v192, v36
	s_add_u32 s24, s24, s8
	s_addc_u32 s25, s25, s9
	s_add_u32 s50, s50, s8
	s_addc_u32 s51, s51, s9
	s_waitcnt lgkmcnt(0)
	v_add_f32_e32 v36, v36, v37
	ds_bpermute_b32 v37, v193, v36
	s_cmpk_lt_i32 s0, 0x2200
	s_waitcnt lgkmcnt(0)
	v_add_f32_e32 v36, v36, v37
	ds_bpermute_b32 v37, v194, v36
	s_waitcnt lgkmcnt(0)
	v_add_f32_e32 v36, v36, v37
	ds_bpermute_b32 v37, v195, v36
	s_waitcnt lgkmcnt(0)
	v_add_f32_e32 v36, v36, v37
	ds_bpermute_b32 v37, v196, v36
	s_waitcnt lgkmcnt(0)
	v_add_f32_e32 v36, v36, v37
	ds_bpermute_b32 v37, v197, v36
	s_waitcnt lgkmcnt(0)
	v_add_f32_e32 v36, v36, v37
	v_fmamk_f32 v36, v36, 0x3a000000, v206
	v_mul_f32_e32 v37, 0x4b800000, v36
	v_cmp_gt_f32_e32 vcc, s1, v36
	s_nop 1
	v_cndmask_b32_e32 v36, v36, v37, vcc
	v_rsq_f32_e32 v38, v36
	v_lshl_add_u64 v[36:37], v[190:191], 0, s[6:7]
	v_lshl_add_u64 v[190:191], v[190:191], 0, s[8:9]
	v_mul_f32_e32 v39, 0x45800000, v38
	v_cndmask_b32_e32 v38, v38, v39, vcc
	v_pk_mul_f32 v[28:29], v[28:29], v[38:39] op_sel_hi:[1,0]
	v_pk_mul_f32 v[30:31], v[30:31], v[38:39] op_sel_hi:[1,0]
	v_pk_mul_f32 v[26:27], v[26:27], v[38:39] op_sel_hi:[1,0]
	v_pk_mul_f32 v[24:25], v[24:25], v[38:39] op_sel_hi:[1,0]
	v_pk_mul_f32 v[22:23], v[22:23], v[38:39] op_sel_hi:[1,0]
	v_pk_mul_f32 v[20:21], v[20:21], v[38:39] op_sel_hi:[1,0]
	v_pk_mul_f32 v[18:19], v[18:19], v[38:39] op_sel_hi:[1,0]
	v_pk_mul_f32 v[16:17], v[16:17], v[38:39] op_sel_hi:[1,0]
	v_pk_mul_f32 v[14:15], v[14:15], v[38:39] op_sel_hi:[1,0]
	v_pk_mul_f32 v[12:13], v[12:13], v[38:39] op_sel_hi:[1,0]
	v_pk_mul_f32 v[10:11], v[10:11], v[38:39] op_sel_hi:[1,0]
	v_pk_mul_f32 v[8:9], v[8:9], v[38:39] op_sel_hi:[1,0]
	v_pk_mul_f32 v[6:7], v[6:7], v[38:39] op_sel_hi:[1,0]
	v_pk_mul_f32 v[4:5], v[4:5], v[38:39] op_sel_hi:[1,0]
	v_pk_mul_f32 v[2:3], v[2:3], v[38:39] op_sel_hi:[1,0]
	v_pk_mul_f32 v[0:1], v[0:1], v[38:39] op_sel_hi:[1,0]
	s_waitcnt vmcnt(0)
	v_pk_mul_f32 v[28:29], v[228:229], v[28:29]
	v_pk_mul_f32 v[30:31], v[230:231], v[30:31]
	global_store_dwordx4 v[36:37], v[28:31], off
	v_pk_mul_f32 v[24:25], v[232:233], v[24:25]
	v_pk_mul_f32 v[26:27], v[234:235], v[26:27]
	global_store_dwordx4 v[36:37], v[24:27], off offset:1024
	v_pk_mul_f32 v[20:21], v[236:237], v[20:21]
	v_pk_mul_f32 v[22:23], v[238:239], v[22:23]
	global_store_dwordx4 v[36:37], v[20:23], off offset:2048
	v_pk_mul_f32 v[16:17], v[240:241], v[16:17]
	v_pk_mul_f32 v[18:19], v[242:243], v[18:19]
	global_store_dwordx4 v[36:37], v[16:19], off offset:3072
	v_add_co_u32_e32 v52, vcc, s5, v36
	s_nop 1
	v_addc_co_u32_e32 v53, vcc, 0, v37, vcc
	v_pk_mul_f32 v[12:13], v[32:33], v[12:13]
	v_pk_mul_f32 v[14:15], v[34:35], v[14:15]
	global_store_dwordx4 v[52:53], v[12:15], off
	v_pk_mul_f32 v[8:9], v[40:41], v[8:9]
	v_pk_mul_f32 v[10:11], v[42:43], v[10:11]
	global_store_dwordx4 v[52:53], v[8:11], off offset:1024
	v_pk_mul_f32 v[4:5], v[44:45], v[4:5]
	v_pk_mul_f32 v[6:7], v[46:47], v[6:7]
	global_store_dwordx4 v[52:53], v[4:7], off offset:2048
	v_pk_mul_f32 v[0:1], v[48:49], v[0:1]
	v_pk_mul_f32 v[2:3], v[50:51], v[2:3]
	global_store_dwordx4 v[52:53], v[0:3], off offset:3072
	s_cbranch_scc0 .LBB0_1244
; __device__ __forceinline__ void final_norm_phase(const Frame& F, int rlo) {
;     ...
;     for (int r = rlo + F.bid * 8 + F.wave; r < MTOT; r += F.G * 8) { f32x4* xr = (f32x4*)(F.out + (size_t)r * D);
;         const f32x4* sr = r < SP ? xr : (const f32x4*)(F.ws + WS_X1) + (size_t)r * (D / 4);
;         f32x4 xv[8]; float ss = 0.f;
; #pragma unroll
;         for (int i = 0; i < 8; ++i) xv[i] = sr[i * 64 + F.lane];
;         if (r >= SP) { for (int z = 0; z < 11; ++z) { const f32x4* pp = (const f32x4*)(F.ws + WS_PART) + ((size_t)z * MS + (r - SP)) * (D / 4);
; #pragma unroll
;                 for (int i = 0; i < 8; ++i) xv[i] += pp[i * 64 + F.lane]; } }
.LBB0_1242:
	s_add_u32 s2, s50, s6
	s_addc_u32 s12, s51, s7
	s_add_u32 s13, s24, s6
	s_addc_u32 s14, s25, s7
	s_cmpk_lt_i32 s0, 0x2000
	s_cselect_b64 s[10:11], -1, 0
	s_and_b64 vcc, s[10:11], exec
	s_cselect_b32 s11, s12, s14
	s_cselect_b32 s10, s2, s13
	global_load_dwordx4 v[28:31], v198, s[10:11]
	global_load_dwordx4 v[24:27], v198, s[10:11] offset:1024
	global_load_dwordx4 v[20:23], v198, s[10:11] offset:2048
	global_load_dwordx4 v[16:19], v198, s[10:11] offset:3072
	global_load_dwordx4 v[12:15], v199, s[10:11]
	global_load_dwordx4 v[8:11], v200, s[10:11]
	global_load_dwordx4 v[4:7], v201, s[10:11]
	global_load_dwordx4 v[0:3], v202, s[10:11]
	global_load_dwordx4 v[228:231], v[180:181], off
	global_load_dwordx4 v[232:235], v[180:181], off offset:1024
	global_load_dwordx4 v[236:239], v[180:181], off offset:2048
	global_load_dwordx4 v[240:243], v[180:181], off offset:3072
	s_cbranch_vccnz .LBB0_1241
	s_add_i32 s2, s0, 0xffffe000
	s_lshl_b64 s[10:11], s[2:3], 13
	s_add_u32 s10, s26, s10
	s_addc_u32 s11, s27, s11
	s_add_u32 s12, s10, 0x400000
	s_addc_u32 s13, s11, 0
	global_load_dwordx4 v[32:35], v198, s[10:11]
	global_load_dwordx4 v[36:39], v198, s[10:11] offset:1024
	global_load_dwordx4 v[40:43], v198, s[10:11] offset:2048
	global_load_dwordx4 v[44:47], v198, s[10:11] offset:3072
	global_load_dwordx4 v[48:51], v199, s[10:11]
	global_load_dwordx4 v[52:55], v200, s[10:11]
	global_load_dwordx4 v[56:59], v201, s[10:11]
	global_load_dwordx4 v[60:63], v202, s[10:11]
	global_load_dwordx4 v[64:67], v198, s[12:13]
	global_load_dwordx4 v[68:71], v203, s[12:13]
	global_load_dwordx4 v[72:75], v204, s[12:13]
	global_load_dwordx4 v[76:79], v205, s[12:13]
	global_load_dwordx4 v[80:83], v199, s[12:13]
	global_load_dwordx4 v[84:87], v200, s[12:13]
	global_load_dwordx4 v[88:91], v201, s[12:13]
	global_load_dwordx4 v[92:95], v202, s[12:13]
	s_add_u32 s12, s10, 0x800000
	s_addc_u32 s13, s11, 0
	global_load_dwordx4 v[96:99], v198, s[12:13]
	global_load_dwordx4 v[100:103], v203, s[12:13]
	global_load_dwordx4 v[104:107], v204, s[12:13]
	global_load_dwordx4 v[108:111], v205, s[12:13]
	global_load_dwordx4 v[112:115], v199, s[12:13]
	global_load_dwordx4 v[116:119], v200, s[12:13]
	global_load_dwordx4 v[120:123], v201, s[12:13]
	global_load_dwordx4 v[124:127], v202, s[12:13]
	s_add_u32 s14, s10, 0xc00000
	s_addc_u32 s15, s11, 0
	s_add_u32 s12, s10, 0x1000000
	s_addc_u32 s13, s11, 0
	global_load_dwordx4 v[128:131], v198, s[14:15]
	global_load_dwordx4 v[132:135], v199, s[14:15]
	global_load_dwordx4 v[136:139], v200, s[14:15]
	global_load_dwordx4 v[140:143], v201, s[14:15]
	global_load_dwordx4 v[144:147], v202, s[14:15]
	global_load_dwordx4 v[148:151], v198, s[12:13]
	global_load_dwordx4 v[168:171], v203, s[14:15]
	global_load_dwordx4 v[152:155], v203, s[12:13]
	global_load_dwordx4 v[172:175], v204, s[14:15]
	global_load_dwordx4 v[156:159], v204, s[12:13]
	global_load_dwordx4 v[176:179], v205, s[14:15]
	global_load_dwordx4 v[160:163], v205, s[12:13]
	global_load_dwordx4 v[164:167], v199, s[12:13]
	s_add_u32 s14, s10, 0x1400000
	s_addc_u32 s15, s11, 0
	s_add_u32 s16, s10, 0x1800000
	s_addc_u32 s17, s11, 0
	s_add_u32 s18, s10, 0x1c00000
	s_addc_u32 s19, s11, 0
	s_add_u32 s20, s10, 0x2000000
	s_addc_u32 s21, s11, 0
	s_add_u32 s22, s10, 0x2400000
	s_addc_u32 s23, s11, 0
	s_add_u32 s10, s10, 0x2800000
	s_addc_u32 s11, s11, 0
	global_load_dwordx4 v[208:211], v199, s[10:11]
	global_load_dwordx4 v[212:215], v201, s[10:11]
	s_waitcnt vmcnt(38)
	v_pk_add_f32 v[30:31], v[30:31], v[34:35]
	v_pk_add_f32 v[28:29], v[28:29], v[32:33]
	s_waitcnt vmcnt(37)
	v_pk_add_f32 v[24:25], v[24:25], v[36:37]
	s_waitcnt vmcnt(36)
	v_pk_add_f32 v[22:23], v[22:23], v[42:43]
	v_pk_add_f32 v[20:21], v[20:21], v[40:41]
	s_waitcnt vmcnt(35)
	v_pk_add_f32 v[18:19], v[18:19], v[46:47]
	s_waitcnt vmcnt(32)
	v_pk_add_f32 v[6:7], v[6:7], v[58:59]
	v_pk_add_f32 v[32:33], v[4:5], v[56:57]
	s_waitcnt vmcnt(31)
	v_pk_add_f32 v[34:35], v[2:3], v[62:63]
	v_pk_add_f32 v[36:37], v[0:1], v[60:61]
	v_pk_add_f32 v[26:27], v[26:27], v[38:39]
	v_pk_add_f32 v[16:17], v[16:17], v[44:45]
	v_pk_add_f32 v[14:15], v[14:15], v[50:51]
	v_pk_add_f32 v[12:13], v[12:13], v[48:49]
	v_pk_add_f32 v[10:11], v[10:11], v[54:55]
	v_pk_add_f32 v[8:9], v[8:9], v[52:53]
	s_waitcnt vmcnt(30)
	v_pk_add_f32 v[30:31], v[30:31], v[66:67]
	v_pk_add_f32 v[28:29], v[28:29], v[64:65]
	s_waitcnt vmcnt(28)
	v_pk_add_f32 v[22:23], v[22:23], v[74:75]
	v_pk_add_f32 v[20:21], v[20:21], v[72:73]
	s_waitcnt vmcnt(27)
	v_pk_add_f32 v[38:39], v[18:19], v[78:79]
	global_load_dwordx4 v[0:3], v200, s[12:13]
	s_waitcnt vmcnt(25)
	v_pk_add_f32 v[50:51], v[6:7], v[90:91]
	global_load_dwordx4 v[4:7], v201, s[12:13]
	v_pk_add_f32 v[32:33], v[32:33], v[88:89]
	s_waitcnt vmcnt(25)
	v_pk_add_f32 v[34:35], v[34:35], v[94:95]
	v_pk_add_f32 v[36:37], v[36:37], v[92:93]
	v_pk_add_f32 v[26:27], v[26:27], v[70:71]
	v_pk_add_f32 v[24:25], v[24:25], v[68:69]
	v_pk_add_f32 v[40:41], v[16:17], v[76:77]
	v_pk_add_f32 v[42:43], v[14:15], v[82:83]
	v_pk_add_f32 v[44:45], v[12:13], v[80:81]
	v_pk_add_f32 v[46:47], v[10:11], v[86:87]
	v_pk_add_f32 v[48:49], v[8:9], v[84:85]
	global_load_dwordx4 v[8:11], v202, s[12:13]
	s_waitcnt vmcnt(25)
	v_pk_add_f32 v[52:53], v[30:31], v[98:99]
	v_pk_add_f32 v[54:55], v[28:29], v[96:97]
	global_load_dwordx4 v[12:15], v198, s[14:15]
	s_waitcnt vmcnt(24)
	v_pk_add_f32 v[60:61], v[22:23], v[106:107]
	v_pk_add_f32 v[62:63], v[20:21], v[104:105]
	global_load_dwordx4 v[16:19], v203, s[14:15]
	s_waitcnt vmcnt(24)
	v_pk_add_f32 v[64:65], v[38:39], v[110:111]
	global_load_dwordx4 v[20:23], v204, s[14:15]
	s_waitcnt vmcnt(22)
; __device__ __forceinline__ void final_norm_phase(const Frame& F, int rlo) {
;     ...
;         if (r >= SP) { for (int z = 0; z < 11; ++z) { const f32x4* pp = (const f32x4*)(F.ws + WS_PART) + ((size_t)z * MS + (r - SP)) * (D / 4);
; #pragma unroll
;                 for (int i = 0; i < 8; ++i) xv[i] += pp[i * 64 + F.lane]; } }
	v_pk_add_f32 v[78:79], v[32:33], v[120:121]
	s_waitcnt vmcnt(21)
	v_pk_add_f32 v[80:81], v[34:35], v[126:127]
	global_load_dwordx4 v[28:31], v199, s[14:15]
	v_pk_add_f32 v[84:85], v[36:37], v[124:125]
	global_load_dwordx4 v[32:35], v200, s[14:15]
	global_load_dwordx4 v[36:39], v201, s[14:15]
	v_pk_add_f32 v[56:57], v[26:27], v[102:103]
	v_pk_add_f32 v[58:59], v[24:25], v[100:101]
	global_load_dwordx4 v[24:27], v205, s[14:15]
	v_pk_add_f32 v[66:67], v[40:41], v[108:109]
	v_pk_add_f32 v[68:69], v[42:43], v[114:115]
	v_pk_add_f32 v[70:71], v[44:45], v[112:113]
	v_pk_add_f32 v[72:73], v[46:47], v[118:119]
	v_pk_add_f32 v[74:75], v[48:49], v[116:117]
	global_load_dwordx4 v[40:43], v202, s[14:15]
	v_pk_add_f32 v[76:77], v[50:51], v[122:123]
	s_waitcnt vmcnt(25)
	v_pk_add_f32 v[88:89], v[52:53], v[130:131]
	v_pk_add_f32 v[92:93], v[54:55], v[128:129]
	s_waitcnt vmcnt(19)
	v_pk_add_f32 v[96:97], v[56:57], v[170:171]
	v_pk_add_f32 v[100:101], v[58:59], v[168:169]
	s_waitcnt vmcnt(17)
	v_pk_add_f32 v[104:105], v[60:61], v[174:175]
	v_pk_add_f32 v[108:109], v[62:63], v[172:173]
	global_load_dwordx4 v[44:47], v198, s[16:17]
	s_waitcnt vmcnt(16)
	v_pk_add_f32 v[112:113], v[64:65], v[178:179]
	global_load_dwordx4 v[48:51], v203, s[16:17]
	v_pk_add_f32 v[116:117], v[66:67], v[176:177]
	global_load_dwordx4 v[52:55], v204, s[16:17]
	v_pk_add_f32 v[120:121], v[68:69], v[134:135]
	global_load_dwordx4 v[56:59], v205, s[16:17]
	v_pk_add_f32 v[124:125], v[70:71], v[132:133]
	global_load_dwordx4 v[60:63], v199, s[16:17]
	v_pk_add_f32 v[128:129], v[72:73], v[138:139]
	global_load_dwordx4 v[64:67], v200, s[16:17]
	v_pk_add_f32 v[132:133], v[74:75], v[136:137]
	global_load_dwordx4 v[68:71], v201, s[16:17]
	global_load_dwordx4 v[72:75], v202, s[16:17]
	v_pk_add_f32 v[134:135], v[76:77], v[142:143]
	v_pk_add_f32 v[136:137], v[78:79], v[140:141]
	global_load_dwordx4 v[76:79], v198, s[18:19]
	v_pk_add_f32 v[138:139], v[80:81], v[146:147]
	global_load_dwordx4 v[80:83], v203, s[18:19]
	v_pk_add_f32 v[140:141], v[84:85], v[144:145]
	global_load_dwordx4 v[84:87], v204, s[18:19]
	v_pk_add_f32 v[142:143], v[88:89], v[150:151]
	global_load_dwordx4 v[88:91], v205, s[18:19]
	v_pk_add_f32 v[144:145], v[92:93], v[148:149]
	global_load_dwordx4 v[92:95], v199, s[18:19]
	v_pk_add_f32 v[146:147], v[96:97], v[154:155]
	global_load_dwordx4 v[96:99], v200, s[18:19]
	v_pk_add_f32 v[148:149], v[100:101], v[152:153]
	global_load_dwordx4 v[100:103], v201, s[18:19]
	v_pk_add_f32 v[150:151], v[104:105], v[158:159]
	global_load_dwordx4 v[104:107], v202, s[18:19]
	v_pk_add_f32 v[152:153], v[108:109], v[156:157]
	global_load_dwordx4 v[108:111], v198, s[20:21]
	s_waitcnt vmcnt(31)
	v_pk_add_f32 v[154:155], v[112:113], v[162:163]
	global_load_dwordx4 v[112:115], v203, s[20:21]
	v_pk_add_f32 v[156:157], v[116:117], v[160:161]
	global_load_dwordx4 v[116:119], v204, s[20:21]
	s_waitcnt vmcnt(32)
	v_pk_add_f32 v[160:161], v[120:121], v[166:167]
	global_load_dwordx4 v[120:123], v205, s[20:21]
	v_pk_add_f32 v[164:165], v[124:125], v[164:165]
	global_load_dwordx4 v[124:127], v199, s[20:21]
	s_waitcnt vmcnt(31)
	v_pk_add_f32 v[166:167], v[128:129], v[2:3]
	global_load_dwordx4 v[128:131], v200, s[20:21]
	v_pk_add_f32 v[168:169], v[132:133], v[0:1]
	global_load_dwordx4 v[0:3], v201, s[20:21]
	s_waitcnt vmcnt(32)
	v_pk_add_f32 v[170:171], v[134:135], v[6:7]
	global_load_dwordx4 v[132:135], v202, s[20:21]
	v_pk_add_f32 v[172:173], v[136:137], v[4:5]
	global_load_dwordx4 v[4:7], v198, s[22:23]
	s_waitcnt vmcnt(31)
	v_pk_add_f32 v[218:219], v[146:147], v[18:19]
	v_pk_add_f32 v[220:221], v[148:149], v[16:17]
	global_load_dwordx4 v[16:19], v201, s[22:23]
	s_waitcnt vmcnt(31)
	v_pk_add_f32 v[222:223], v[150:151], v[22:23]
	global_load_dwordx4 v[148:151], v202, s[22:23]
	v_pk_add_f32 v[224:225], v[152:153], v[20:21]
	global_load_dwordx4 v[20:23], v198, s[10:11]
	v_pk_add_f32 v[178:179], v[142:143], v[14:15]
	v_pk_add_f32 v[216:217], v[144:145], v[12:13]
	global_load_dwordx4 v[12:15], v199, s[22:23]
	global_load_dwordx4 v[144:147], v200, s[22:23]
	s_waitcnt vmcnt(34)
	v_pk_add_f32 v[28:29], v[164:165], v[28:29]
	s_waitcnt vmcnt(33)
	v_pk_add_f32 v[164:165], v[166:167], v[34:35]
	v_pk_add_f32 v[166:167], v[168:169], v[32:33]
	s_waitcnt vmcnt(32)
	v_pk_add_f32 v[168:169], v[170:171], v[38:39]
	v_pk_add_f32 v[170:171], v[172:173], v[36:37]
	global_load_dwordx4 v[36:39], v202, s[10:11]
	v_pk_add_f32 v[174:175], v[138:139], v[10:11]
	global_load_dwordx4 v[136:139], v203, s[22:23]
	v_pk_add_f32 v[176:177], v[140:141], v[8:9]
	global_load_dwordx4 v[8:11], v204, s[22:23]
	global_load_dwordx4 v[140:143], v205, s[22:23]
	s_waitcnt vmcnt(35)
; __device__ __forceinline__ void final_norm_phase(const Frame& F, int rlo) {
;     ...
;         if (r >= SP) { for (int z = 0; z < 11; ++z) { const f32x4* pp = (const f32x4*)(F.ws + WS_PART) + ((size_t)z * MS + (r - SP)) * (D / 4);
; #pragma unroll
;                 for (int i = 0; i < 8; ++i) xv[i] += pp[i * 64 + F.lane]; } }
	v_pk_add_f32 v[26:27], v[154:155], v[26:27]
	global_load_dwordx4 v[152:155], v203, s[10:11]
	v_pk_add_f32 v[24:25], v[156:157], v[24:25]
	global_load_dwordx4 v[156:159], v204, s[10:11]
	v_pk_add_f32 v[30:31], v[160:161], v[30:31]
	global_load_dwordx4 v[160:163], v205, s[10:11]
	global_load_dwordx4 v[32:35], v200, s[10:11]
	s_waitcnt vmcnt(38)
	v_pk_add_f32 v[42:43], v[174:175], v[42:43]
	v_pk_add_f32 v[40:41], v[176:177], v[40:41]
	s_waitcnt vmcnt(37)
	v_pk_add_f32 v[46:47], v[178:179], v[46:47]
	v_pk_add_f32 v[44:45], v[216:217], v[44:45]
	s_waitcnt vmcnt(36)
	v_pk_add_f32 v[50:51], v[218:219], v[50:51]
	v_pk_add_f32 v[48:49], v[220:221], v[48:49]
	s_waitcnt vmcnt(35)
	v_pk_add_f32 v[54:55], v[222:223], v[54:55]
	v_pk_add_f32 v[52:53], v[224:225], v[52:53]
	s_waitcnt vmcnt(34)
	v_pk_add_f32 v[26:27], v[26:27], v[58:59]
	v_pk_add_f32 v[24:25], v[24:25], v[56:57]
	s_waitcnt vmcnt(33)
	v_pk_add_f32 v[30:31], v[30:31], v[62:63]
	v_pk_add_f32 v[28:29], v[28:29], v[60:61]
	s_waitcnt vmcnt(32)
	v_pk_add_f32 v[56:57], v[164:165], v[66:67]
	v_pk_add_f32 v[58:59], v[166:167], v[64:65]
	s_waitcnt vmcnt(31)
	v_pk_add_f32 v[60:61], v[168:169], v[70:71]
	v_pk_add_f32 v[62:63], v[170:171], v[68:69]
	s_waitcnt vmcnt(30)
	v_pk_add_f32 v[42:43], v[42:43], v[74:75]
	v_pk_add_f32 v[40:41], v[40:41], v[72:73]
	s_waitcnt vmcnt(29)
	v_pk_add_f32 v[46:47], v[46:47], v[78:79]
	v_pk_add_f32 v[44:45], v[44:45], v[76:77]
	s_waitcnt vmcnt(28)
	v_pk_add_f32 v[50:51], v[50:51], v[82:83]
	v_pk_add_f32 v[48:49], v[48:49], v[80:81]
	s_waitcnt vmcnt(27)
	v_pk_add_f32 v[54:55], v[54:55], v[86:87]
	v_pk_add_f32 v[52:53], v[52:53], v[84:85]
	s_waitcnt vmcnt(26)
	v_pk_add_f32 v[26:27], v[26:27], v[90:91]
	v_pk_add_f32 v[24:25], v[24:25], v[88:89]
	s_waitcnt vmcnt(25)
	v_pk_add_f32 v[30:31], v[30:31], v[94:95]
	v_pk_add_f32 v[28:29], v[28:29], v[92:93]
	s_waitcnt vmcnt(24)
	v_pk_add_f32 v[56:57], v[56:57], v[98:99]
	v_pk_add_f32 v[58:59], v[58:59], v[96:97]
	s_waitcnt vmcnt(23)
	v_pk_add_f32 v[60:61], v[60:61], v[102:103]
	v_pk_add_f32 v[62:63], v[62:63], v[100:101]
	s_waitcnt vmcnt(22)
	v_pk_add_f32 v[42:43], v[42:43], v[106:107]
	v_pk_add_f32 v[40:41], v[40:41], v[104:105]
	s_waitcnt vmcnt(21)
	v_pk_add_f32 v[46:47], v[46:47], v[110:111]
	v_pk_add_f32 v[44:45], v[44:45], v[108:109]
	s_waitcnt vmcnt(20)
	v_pk_add_f32 v[50:51], v[50:51], v[114:115]
	v_pk_add_f32 v[48:49], v[48:49], v[112:113]
	s_waitcnt vmcnt(19)
	v_pk_add_f32 v[54:55], v[54:55], v[118:119]
	v_pk_add_f32 v[52:53], v[52:53], v[116:117]
	s_waitcnt vmcnt(18)
	v_pk_add_f32 v[26:27], v[26:27], v[122:123]
	v_pk_add_f32 v[24:25], v[24:25], v[120:121]
	s_waitcnt vmcnt(17)
	v_pk_add_f32 v[30:31], v[30:31], v[126:127]
	v_pk_add_f32 v[28:29], v[28:29], v[124:125]
	s_waitcnt vmcnt(16)
	v_pk_add_f32 v[56:57], v[56:57], v[130:131]
	v_pk_add_f32 v[58:59], v[58:59], v[128:129]
	s_waitcnt vmcnt(15)
	v_pk_add_f32 v[2:3], v[60:61], v[2:3]
	v_pk_add_f32 v[0:1], v[62:63], v[0:1]
	s_waitcnt vmcnt(14)
	v_pk_add_f32 v[42:43], v[42:43], v[134:135]
	v_pk_add_f32 v[40:41], v[40:41], v[132:133]
	s_waitcnt vmcnt(13)
	v_pk_add_f32 v[6:7], v[46:47], v[6:7]
	v_pk_add_f32 v[4:5], v[44:45], v[4:5]
	s_waitcnt vmcnt(12)
	v_pk_add_f32 v[2:3], v[2:3], v[18:19]
	v_pk_add_f32 v[0:1], v[0:1], v[16:17]
	s_waitcnt vmcnt(11)
	v_pk_add_f32 v[42:43], v[42:43], v[150:151]
	v_pk_add_f32 v[40:41], v[40:41], v[148:149]
	s_waitcnt vmcnt(9)
	v_pk_add_f32 v[14:15], v[30:31], v[14:15]
	v_pk_add_f32 v[12:13], v[28:29], v[12:13]
	v_pk_add_f32 v[30:31], v[6:7], v[22:23]
	v_pk_add_f32 v[28:29], v[4:5], v[20:21]
	v_pk_add_f32 v[14:15], v[14:15], v[210:211]
	v_pk_add_f32 v[12:13], v[12:13], v[208:209]
	v_pk_add_f32 v[6:7], v[2:3], v[214:215]
	v_pk_add_f32 v[4:5], v[0:1], v[212:213]
	s_waitcnt vmcnt(7)
	v_pk_add_f32 v[2:3], v[42:43], v[38:39]
	s_waitcnt vmcnt(6)
	v_pk_add_f32 v[44:45], v[50:51], v[138:139]
	v_pk_add_f32 v[46:47], v[48:49], v[136:137]
	s_waitcnt vmcnt(5)
	v_pk_add_f32 v[10:11], v[54:55], v[10:11]
	v_pk_add_f32 v[8:9], v[52:53], v[8:9]
	s_waitcnt vmcnt(4)
	v_pk_add_f32 v[48:49], v[26:27], v[142:143]
	v_pk_add_f32 v[50:51], v[24:25], v[140:141]
	v_pk_add_f32 v[52:53], v[56:57], v[146:147]
	v_pk_add_f32 v[54:55], v[58:59], v[144:145]
	s_waitcnt vmcnt(3)
	v_pk_add_f32 v[26:27], v[44:45], v[154:155]
	v_pk_add_f32 v[24:25], v[46:47], v[152:153]
	s_waitcnt vmcnt(2)
	v_pk_add_f32 v[22:23], v[10:11], v[158:159]
	v_pk_add_f32 v[20:21], v[8:9], v[156:157]
	s_waitcnt vmcnt(1)
	v_pk_add_f32 v[18:19], v[48:49], v[162:163]
	v_pk_add_f32 v[16:17], v[50:51], v[160:161]
	s_waitcnt vmcnt(0)
	v_pk_add_f32 v[10:11], v[52:53], v[34:35]
	v_pk_add_f32 v[8:9], v[54:55], v[32:33]
	v_pk_add_f32 v[0:1], v[40:41], v[36:37]
	s_branch .LBB0_1241
